# P2 tiles: add/rcp/mask/suffix-product/e*P stages interleaved one key apart (same instructions and arithmetic order, no back-to-back dependent VALU)
# baseline (speedup 1.0000x reference)
; template <bool DIAG>
; __device__ __forceinline__ void sb_tile(const bf16x8 (&kf)[4], const bf16x8 (&vf)[4], const bf16x8 (&qf)[4], f32x16& o0, f32x16& o1, float& c, int rel0, int hi) {
;     f32x16 s;
; #pragma unroll
;     for (int r = 0; r < 16; ++r) s[r] = 0.f;
; #pragma unroll
;     for (int d0 = 0; d0 < 4; ++d0) s = __builtin_amdgcn_mfma_f32_32x32x16_bf16(kf[d0], qf[d0], s, 0, 0, 0);
;     float L[16]; float tot = 0.f;
; #pragma unroll
;     for (int r = 15; r >= 0; --r) {
;         const float z = s[r];
;         const float sp = fmaxf(z, 0.f) + __builtin_amdgcn_logf(1.0f + __builtin_amdgcn_exp2f(-fabsf(z)));
;         if (DIAG) tot += (r < rel0) ? -sp : 0.f; else tot -= sp;
;         L[r] = tot;
;     }
;     const float tot_o = __shfl_xor(tot, 32);
;     const float add = c + (hi == 0 ? tot_o : 0.f);
;     float w[16];
; #pragma unroll
;     for (int r = 0; r < 16; ++r) {
;         const float e = __builtin_amdgcn_exp2f(s[r] + L[r] + add);
;         w[r] = DIAG ? ((r < rel0) ? e : 0.f) : e;
;     }
;     c += tot + tot_o;
;     u32x4 p0, p1;
; __device__ __forceinline__ void sb_attn_unit(const bf16_t* __restrict__ Q, const bf16_t* __restrict__ Kb, const bf16_t* __restrict__ VT, bf16_t* __restrict__ MIX, int b, int h, int qb, int lane) {
;     const int q = lane & 31, hi = lane >> 5, q0 = qb * 32;
;     const size_t rowbase = (size_t)b * SEQ;
;     bf16x8 qf[4];
;     const size_t hb = (size_t)(b * 8 + h) * 8192;
;     { const bf16_t* qp = Q + (hb + q0 + q) * 64 + 8 * hi;
; #pragma unroll
;       for (int d0 = 0; d0 < 4; ++d0) qf[d0] = *(const bf16x8*)(qp + 16 * d0); }
;     const bf16_t* kp = Kb + hb * 64 + lane * 8;
;     const bf16_t* vp = VT + hb * 64 + lane * 8;
;     f32x16 o0, o1;
; #pragma unroll
;     for (int r = 0; r < 16; ++r) { o0[r] = 0.f; o1[r] = 0.f; }
;     float c = 0.f;
;     bf16x8 kf[4], vf[4], kn[4], vn[4];
; #pragma unroll
;     for (int i = 0; i < 4; ++i) { kf[i] = *(const bf16x8*)(kp + (size_t)q0 * 64 + 512 * i); vf[i] = *(const bf16x8*)(vp + (size_t)q0 * 64 + 512 * i); }
;     int kvn = q0 >= 32 ? q0 - 32 : 0;
; #pragma unroll
;     for (int i = 0; i < 4; ++i) { kn[i] = *(const bf16x8*)(kp + (size_t)kvn * 64 + 512 * i); vn[i] = *(const bf16x8*)(vp + (size_t)kvn * 64 + 512 * i); }
;     sb_tile<true>(kf, vf, qf, o0, o1, c, q - 16 * hi, hi);
.LBB0_353:
	s_ashr_i32 s52, s3, 11
	s_bfe_u32 s60, s3, 0x30008
	s_lshl_b32 s50, s52, 3
	s_or_b32 s54, s50, s60
	s_ashr_i32 s55, s54, 31
	s_and_b32 s53, s3, 0xff
	s_lshl_b64 s[56:57], s[54:55], 13
	s_lshl_b64 s[54:55], s[54:55], 20
	v_lshl_add_u64 v[86:87], v[82:83], 0, s[54:55]
	s_lshl_b32 s50, s53, 12
	v_lshl_add_u64 v[24:25], v[86:87], 0, s[50:51]
	global_load_dwordx4 v[0:3], v[24:25], off
	s_lshl_b32 s61, s53, 5
	s_or_b32 s56, s56, s61
	v_mov_b32_e32 v5, s57
	v_or_b32_e32 v4, s56, v76
	v_lshlrev_b64 v[4:5], 7, v[4:5]
	v_lshl_add_u64 v[30:31], v[80:81], 0, v[4:5]
	global_load_dwordx4 v[48:51], v[30:31], off
	global_load_dwordx4 v[16:19], v[24:25], off offset:1024
	global_load_dwordx4 v[52:55], v[30:31], off offset:32
	global_load_dwordx4 v[20:23], v[24:25], off offset:2048
	global_load_dwordx4 v[56:59], v[30:31], off offset:64
	global_load_dwordx4 v[26:29], v[24:25], off offset:3072
	global_load_dwordx4 v[60:63], v[30:31], off offset:96
	v_lshl_add_u64 v[88:89], v[84:85], 0, s[54:55]
	v_lshl_add_u64 v[24:25], v[88:89], 0, s[50:51]
	s_sub_i32 s50, s61, 32
	s_cmp_lg_u32 s53, 0
	s_cselect_b32 s54, s50, 0
	s_waitcnt vmcnt(0)
	v_mfma_f32_32x32x16_bf16 v[0:15], v[0:3], v[48:51], 0
	v_mfma_f32_32x32x16_bf16 v[0:15], v[16:19], v[52:55], v[0:15]
	v_mfma_f32_32x32x16_bf16 v[0:15], v[20:23], v[56:59], v[0:15]
	global_load_dwordx4 v[20:23], v[24:25], off
	global_load_dwordx4 v[16:19], v[24:25], off offset:1024
	v_mfma_f32_32x32x16_bf16 v[0:15], v[26:29], v[60:63], v[0:15]
	global_load_dwordx4 v[26:29], v[24:25], off offset:2048
	global_load_dwordx4 v[38:41], v[24:25], off offset:3072
	s_nop 9
	v_exp_f32_e32 v15, v15
	v_exp_f32_e32 v14, v14
	v_exp_f32_e32 v13, v13
	v_exp_f32_e32 v12, v12
	v_exp_f32_e32 v11, v11
	v_exp_f32_e32 v10, v10
	v_exp_f32_e32 v9, v9
	v_exp_f32_e32 v8, v8
	v_exp_f32_e32 v7, v7
	v_exp_f32_e32 v6, v6
	v_exp_f32_e32 v5, v5
	v_exp_f32_e32 v4, v4
	v_exp_f32_e32 v3, v3
	v_exp_f32_e32 v2, v2
	v_exp_f32_e32 v1, v1
	v_exp_f32_e32 v0, v0
	v_add_f32_e32 v113, 1.0, v15
	v_add_f32_e32 v112, 1.0, v14
	v_rcp_f32_e32 v113, v113
	v_add_f32_e32 v111, 1.0, v13
	v_rcp_f32_e32 v112, v112
	v_cndmask_b32_e64 v113, 1.0, v113, s[6:7]
	v_add_f32_e32 v110, 1.0, v12
	v_rcp_f32_e32 v111, v111
	v_cndmask_b32_e64 v112, 1.0, v112, s[8:9]
	v_add_f32_e32 v109, 1.0, v11
	v_rcp_f32_e32 v110, v110
	v_cndmask_b32_e64 v111, 1.0, v111, s[10:11]
	v_mul_f32_e32 v112, v112, v113
	v_mul_f32_e32 v15, v15, v113
	v_add_f32_e32 v108, 1.0, v10
	v_rcp_f32_e32 v109, v109
	v_cndmask_b32_e64 v110, 1.0, v110, s[12:13]
	v_mul_f32_e32 v111, v111, v112
	v_mul_f32_e32 v14, v14, v112
	v_add_f32_e32 v107, 1.0, v9
	v_rcp_f32_e32 v108, v108
	v_cndmask_b32_e64 v109, 1.0, v109, s[14:15]
	v_mul_f32_e32 v110, v110, v111
	v_mul_f32_e32 v13, v13, v111
	v_add_f32_e32 v106, 1.0, v8
	v_rcp_f32_e32 v107, v107
	v_cndmask_b32_e64 v108, 1.0, v108, s[16:17]
	v_mul_f32_e32 v109, v109, v110
	v_mul_f32_e32 v12, v12, v110
	v_add_f32_e32 v105, 1.0, v7
	v_rcp_f32_e32 v106, v106
	v_cndmask_b32_e64 v107, 1.0, v107, s[18:19]
	v_mul_f32_e32 v108, v108, v109
	v_mul_f32_e32 v11, v11, v109
	v_add_f32_e32 v104, 1.0, v6
	v_rcp_f32_e32 v105, v105
	v_cndmask_b32_e64 v106, 1.0, v106, s[20:21]
	v_mul_f32_e32 v107, v107, v108
	v_mul_f32_e32 v10, v10, v108
	v_add_f32_e32 v103, 1.0, v5
	v_rcp_f32_e32 v104, v104
	v_cndmask_b32_e64 v105, 1.0, v105, s[22:23]
	v_mul_f32_e32 v106, v106, v107
	v_mul_f32_e32 v9, v9, v107
	v_add_f32_e32 v102, 1.0, v4
	v_rcp_f32_e32 v103, v103
	v_cndmask_b32_e64 v104, 1.0, v104, s[24:25]
	v_mul_f32_e32 v105, v105, v106
	v_mul_f32_e32 v8, v8, v106
	v_add_f32_e32 v101, 1.0, v3
	v_rcp_f32_e32 v102, v102
	v_cndmask_b32_e64 v103, 1.0, v103, s[26:27]
	v_mul_f32_e32 v104, v104, v105
	v_mul_f32_e32 v7, v7, v105
	v_add_f32_e32 v100, 1.0, v2
	v_rcp_f32_e32 v101, v101
	v_cndmask_b32_e64 v102, 1.0, v102, s[28:29]
	v_mul_f32_e32 v103, v103, v104
	v_mul_f32_e32 v6, v6, v104
	v_add_f32_e32 v99, 1.0, v1
	v_rcp_f32_e32 v100, v100
	v_cndmask_b32_e64 v101, 1.0, v101, s[30:31]
	v_mul_f32_e32 v102, v102, v103
	v_mul_f32_e32 v5, v5, v103
	v_add_f32_e32 v98, 1.0, v0
	v_rcp_f32_e32 v99, v99
	v_cndmask_b32_e64 v100, 1.0, v100, s[34:35]
	v_mul_f32_e32 v101, v101, v102
	v_mul_f32_e32 v4, v4, v102
	v_rcp_f32_e32 v98, v98
	v_cndmask_b32_e64 v99, 1.0, v99, s[36:37]
	v_mul_f32_e32 v100, v100, v101
	v_mul_f32_e32 v3, v3, v101
	v_cndmask_b32_e64 v98, 1.0, v98, s[38:39]
	v_mul_f32_e32 v99, v99, v100
	v_mul_f32_e32 v2, v2, v100
	v_mul_f32_e32 v98, v98, v99
	ds_bpermute_b32 v115, v77, v98
	v_mul_f32_e32 v1, v1, v99
	v_mul_f32_e32 v0, v0, v98
	s_waitcnt lgkmcnt(0)
	v_cndmask_b32_e64 v114, 1.0, v115, s[40:41]
	v_mul_f32_e32 v0, v0, v114
	v_mul_f32_e32 v1, v1, v114
	v_mul_f32_e32 v2, v2, v114
	v_mul_f32_e32 v3, v3, v114
	v_mul_f32_e32 v4, v4, v114
	v_mul_f32_e32 v5, v5, v114
	v_mul_f32_e32 v6, v6, v114
	v_mul_f32_e32 v7, v7, v114
	v_mul_f32_e32 v8, v8, v114
	v_mul_f32_e32 v9, v9, v114
	v_mul_f32_e32 v10, v10, v114
	v_mul_f32_e32 v11, v11, v114
	v_mul_f32_e32 v12, v12, v114
	v_mul_f32_e32 v13, v13, v114
	v_mul_f32_e32 v14, v14, v114
	v_mul_f32_e32 v15, v15, v114
	v_cndmask_b32_e64 v0, 0, v0, s[38:39]
	v_cndmask_b32_e64 v1, 0, v1, s[36:37]
	v_cndmask_b32_e64 v2, 0, v2, s[34:35]
	v_cndmask_b32_e64 v3, 0, v3, s[30:31]
	v_cndmask_b32_e64 v4, 0, v4, s[28:29]
	v_cndmask_b32_e64 v5, 0, v5, s[26:27]
	v_cndmask_b32_e64 v6, 0, v6, s[24:25]
	v_cndmask_b32_e64 v7, 0, v7, s[22:23]
	v_cndmask_b32_e64 v8, 0, v8, s[20:21]
	v_cndmask_b32_e64 v9, 0, v9, s[18:19]
	v_cndmask_b32_e64 v10, 0, v10, s[16:17]
	v_cndmask_b32_e64 v11, 0, v11, s[14:15]
	v_cndmask_b32_e64 v12, 0, v12, s[12:13]
	v_cndmask_b32_e64 v13, 0, v13, s[10:11]
	v_cndmask_b32_e64 v14, 0, v14, s[8:9]
	v_cndmask_b32_e64 v15, 0, v15, s[6:7]
	v_cvt_pk_bf16_f32 v30, v0, v1
	v_cvt_pk_bf16_f32 v31, v2, v3
	v_cvt_pk_bf16_f32 v32, v4, v5
	v_cvt_pk_bf16_f32 v33, v6, v7
	v_cvt_pk_bf16_f32 v34, v8, v9
	v_cvt_pk_bf16_f32 v35, v10, v11
	v_cvt_pk_bf16_f32 v36, v12, v13
	v_cvt_pk_bf16_f32 v37, v14, v15
	v_mul_f32_e32 v120, v98, v115
	v_log_f32_e32 v120, v120
	s_waitcnt vmcnt(0)
	v_mfma_f32_32x32x16_bf16 v[0:15], v[20:23], v[30:33], 0
	v_mfma_f32_32x32x16_bf16 v[0:15], v[16:19], v[34:37], v[0:15]
	v_mfma_f32_32x32x16_bf16 v[16:31], v[26:29], v[30:33], 0
	v_add_f32_e32 v90, 0, v120
	v_mfma_f32_32x32x16_bf16 v[16:31], v[38:41], v[34:37], v[16:31]
	s_branch .LBB0_355
; template <bool DIAG>
; __device__ __forceinline__ void sb_tile(const bf16x8 (&kf)[4], const bf16x8 (&vf)[4], const bf16x8 (&qf)[4], f32x16& o0, f32x16& o1, float& c, int rel0, int hi) {
;     f32x16 s;
; #pragma unroll
;     for (int r = 0; r < 16; ++r) s[r] = 0.f;
; #pragma unroll
;     for (int d0 = 0; d0 < 4; ++d0) s = __builtin_amdgcn_mfma_f32_32x32x16_bf16(kf[d0], qf[d0], s, 0, 0, 0);
;     float L[16]; float tot = 0.f;
; #pragma unroll
;     for (int r = 15; r >= 0; --r) {
;         const float z = s[r];
;         const float sp = fmaxf(z, 0.f) + __builtin_amdgcn_logf(1.0f + __builtin_amdgcn_exp2f(-fabsf(z)));
;         if (DIAG) tot += (r < rel0) ? -sp : 0.f; else tot -= sp;
;         L[r] = tot;
;     }
;     const float tot_o = __shfl_xor(tot, 32);
;     const float add = c + (hi == 0 ? tot_o : 0.f);
;     float w[16];
; #pragma unroll
;     for (int r = 0; r < 16; ++r) {
;         const float e = __builtin_amdgcn_exp2f(s[r] + L[r] + add);
;         w[r] = DIAG ? ((r < rel0) ? e : 0.f) : e;
;     }
;     c += tot + tot_o;
;     u32x4 p0, p1;
;     p0.x = cvt_pk_bf16(w[0], w[1]); p0.y = cvt_pk_bf16(w[2], w[3]); p0.z = cvt_pk_bf16(w[4], w[5]); p0.w = cvt_pk_bf16(w[6], w[7]);
;     p1.x = cvt_pk_bf16(w[8], w[9]); p1.y = cvt_pk_bf16(w[10], w[11]); p1.z = cvt_pk_bf16(w[12], w[13]); p1.w = cvt_pk_bf16(w[14], w[15]);
;     const bf16x8 pf0 = __builtin_bit_cast(bf16x8, p0), pf1 = __builtin_bit_cast(bf16x8, p1);
;     o0 = __builtin_amdgcn_mfma_f32_32x32x16_bf16(vf[0], pf0, o0, 0, 0, 0);
;     o0 = __builtin_amdgcn_mfma_f32_32x32x16_bf16(vf[1], pf1, o0, 0, 0, 0);
;     o1 = __builtin_amdgcn_mfma_f32_32x32x16_bf16(vf[2], pf0, o1, 0, 0, 0);
; __device__ __forceinline__ void sb_attn_unit(const bf16_t* __restrict__ Q, const bf16_t* __restrict__ Kb, const bf16_t* __restrict__ VT, bf16_t* __restrict__ MIX, int b, int h, int qb, int lane) {
;     ...
;     for (int kv0 = q0 - 32; kv0 >= 0; kv0 -= 32) {
; #pragma unroll
;         for (int i = 0; i < 4; ++i) { kf[i] = kn[i]; vf[i] = vn[i]; }
;         kvn = kv0 >= 32 ? kv0 - 32 : 0;
; #pragma unroll
;         for (int i = 0; i < 4; ++i) { kn[i] = *(const bf16x8*)(kp + (size_t)kvn * 64 + 512 * i); vn[i] = *(const bf16x8*)(vp + (size_t)kvn * 64 + 512 * i); }
;         sb_tile<false>(kf, vf, qf, o0, o1, c, 0, hi);
;         if (__all(c < -150.1f)) break;
;     }
.LBB0_354:
	s_ashr_i32 s55, s54, 31
	s_lshl_b64 s[54:55], s[54:55], 7
	v_lshl_add_u64 v[72:73], v[86:87], 0, s[54:55]
	global_load_dwordx4 v[32:35], v[72:73], off
	global_load_dwordx4 v[64:67], v[72:73], off offset:1024
	global_load_dwordx4 v[68:71], v[72:73], off offset:2048
	global_load_dwordx4 v[94:97], v[72:73], off offset:3072
	v_lshl_add_u64 v[92:93], v[88:89], 0, s[54:55]
	s_sub_i32 s53, s50, 32
	s_cmp_lg_u32 s50, 0
	s_cselect_b32 s54, s53, 0
	s_mov_b32 s50, s53
	s_waitcnt vmcnt(3)
	v_mfma_f32_32x32x16_bf16 v[32:47], v[32:35], v[48:51], 0
	s_waitcnt vmcnt(2)
	v_mfma_f32_32x32x16_bf16 v[32:47], v[64:67], v[52:55], v[32:47]
	s_waitcnt vmcnt(1)
	v_mfma_f32_32x32x16_bf16 v[32:47], v[68:71], v[56:59], v[32:47]
	global_load_dwordx4 v[72:75], v[92:93], off
	global_load_dwordx4 v[68:71], v[92:93], off offset:1024
	global_load_dwordx4 v[64:67], v[92:93], off offset:2048
	s_waitcnt vmcnt(3)
	v_mfma_f32_32x32x16_bf16 v[32:47], v[94:97], v[60:63], v[32:47]
	global_load_dwordx4 v[116:119], v[92:93], off offset:3072
	s_nop 10
	v_exp_f32_e32 v47, v47
	v_exp_f32_e32 v46, v46
	v_exp_f32_e32 v45, v45
	v_exp_f32_e32 v44, v44
	v_exp_f32_e32 v43, v43
	v_exp_f32_e32 v42, v42
	v_exp_f32_e32 v41, v41
	v_exp_f32_e32 v40, v40
	v_exp_f32_e32 v39, v39
	v_exp_f32_e32 v38, v38
	v_exp_f32_e32 v37, v37
	v_exp_f32_e32 v36, v36
	v_exp_f32_e32 v35, v35
	v_exp_f32_e32 v34, v34
	v_exp_f32_e32 v33, v33
	v_exp_f32_e32 v32, v32
	v_exp_f32_e32 v114, v90
	v_add_f32_e32 v113, 1.0, v47
	v_add_f32_e32 v112, 1.0, v46
	v_rcp_f32_e32 v113, v113
	v_add_f32_e32 v111, 1.0, v45
	v_rcp_f32_e32 v112, v112
	v_add_f32_e32 v110, 1.0, v44
	v_rcp_f32_e32 v111, v111
	v_mul_f32_e32 v112, v112, v113
	v_mul_f32_e32 v47, v47, v113
	v_add_f32_e32 v109, 1.0, v43
	v_rcp_f32_e32 v110, v110
	v_mul_f32_e32 v111, v111, v112
	v_mul_f32_e32 v46, v46, v112
	v_add_f32_e32 v108, 1.0, v42
	v_rcp_f32_e32 v109, v109
	v_mul_f32_e32 v110, v110, v111
	v_mul_f32_e32 v45, v45, v111
	v_add_f32_e32 v107, 1.0, v41
	v_rcp_f32_e32 v108, v108
	v_mul_f32_e32 v109, v109, v110
	v_mul_f32_e32 v44, v44, v110
	v_add_f32_e32 v106, 1.0, v40
	v_rcp_f32_e32 v107, v107
	v_mul_f32_e32 v108, v108, v109
	v_mul_f32_e32 v43, v43, v109
	v_add_f32_e32 v105, 1.0, v39
	v_rcp_f32_e32 v106, v106
	v_mul_f32_e32 v107, v107, v108
	v_mul_f32_e32 v42, v42, v108
	v_add_f32_e32 v104, 1.0, v38
	v_rcp_f32_e32 v105, v105
	v_mul_f32_e32 v106, v106, v107
	v_mul_f32_e32 v41, v41, v107
	v_add_f32_e32 v103, 1.0, v37
	v_rcp_f32_e32 v104, v104
	v_mul_f32_e32 v105, v105, v106
	v_mul_f32_e32 v40, v40, v106
	v_add_f32_e32 v102, 1.0, v36
	v_rcp_f32_e32 v103, v103
	v_mul_f32_e32 v104, v104, v105
	v_mul_f32_e32 v39, v39, v105
	v_add_f32_e32 v101, 1.0, v35
	v_rcp_f32_e32 v102, v102
	v_mul_f32_e32 v103, v103, v104
	v_mul_f32_e32 v38, v38, v104
	v_add_f32_e32 v100, 1.0, v34
	v_rcp_f32_e32 v101, v101
	v_mul_f32_e32 v102, v102, v103
	v_mul_f32_e32 v37, v37, v103
	v_add_f32_e32 v99, 1.0, v33
	v_rcp_f32_e32 v100, v100
	v_mul_f32_e32 v101, v101, v102
	v_mul_f32_e32 v36, v36, v102
	v_add_f32_e32 v98, 1.0, v32
	v_rcp_f32_e32 v99, v99
	v_mul_f32_e32 v100, v100, v101
	v_mul_f32_e32 v35, v35, v101
	v_rcp_f32_e32 v98, v98
	v_mul_f32_e32 v99, v99, v100
	v_mul_f32_e32 v34, v34, v100
	v_mul_f32_e32 v98, v98, v99
	ds_bpermute_b32 v115, v77, v98
	v_mul_f32_e32 v33, v33, v99
	v_mul_f32_e32 v32, v32, v98
	s_waitcnt lgkmcnt(0)
	v_cndmask_b32_e64 v120, 1.0, v115, s[40:41]
	v_mul_f32_e32 v114, v114, v120
	v_mul_f32_e32 v32, v32, v114
	v_mul_f32_e32 v33, v33, v114
	v_mul_f32_e32 v34, v34, v114
	v_mul_f32_e32 v35, v35, v114
	v_mul_f32_e32 v36, v36, v114
	v_mul_f32_e32 v37, v37, v114
	v_mul_f32_e32 v38, v38, v114
	v_mul_f32_e32 v39, v39, v114
	v_mul_f32_e32 v40, v40, v114
	v_mul_f32_e32 v41, v41, v114
	v_mul_f32_e32 v42, v42, v114
	v_mul_f32_e32 v43, v43, v114
	v_mul_f32_e32 v44, v44, v114
	v_mul_f32_e32 v45, v45, v114
	v_mul_f32_e32 v46, v46, v114
	v_mul_f32_e32 v47, v47, v114
	v_cvt_pk_bf16_f32 v32, v32, v33
	v_cvt_pk_bf16_f32 v33, v34, v35
	v_cvt_pk_bf16_f32 v34, v36, v37
	v_cvt_pk_bf16_f32 v35, v38, v39
	v_cvt_pk_bf16_f32 v36, v40, v41
	v_cvt_pk_bf16_f32 v37, v42, v43
	v_cvt_pk_bf16_f32 v38, v44, v45
	v_cvt_pk_bf16_f32 v39, v46, v47
	s_waitcnt vmcnt(0)
	v_mfma_f32_32x32x16_bf16 v[0:15], v[72:75], v[32:35], v[0:15]
	v_mfma_f32_32x32x16_bf16 v[16:31], v[64:67], v[32:35], v[16:31]
	v_mul_f32_e32 v120, v98, v115
	v_log_f32_e32 v120, v120
	v_mfma_f32_32x32x16_bf16 v[0:15], v[68:71], v[36:39], v[0:15]
	v_mfma_f32_32x32x16_bf16 v[16:31], v[116:119], v[36:39], v[16:31]
	v_add_f32_e32 v90, v90, v120
	v_cmp_gt_f32_e32 vcc, s59, v90
	s_cmp_eq_u64 vcc, exec
	s_cselect_b64 s[56:57], -1, 0
	s_andn2_b64 vcc, exec, s[56:57]
	s_cbranch_vccz .LBB0_352
